# split (arrive early / wait late) barrier on the two WAR-only seams ffn1down->inproj and crossout->ffn2up
# speedup vs baseline: 1.0538x; 1.0033x over previous
.LBB0_99:
	s_or_b64 exec, exec, s[2:3]
	s_barrier
	v_readlane_b32 s0, v255, 0
	v_readlane_b32 s1, v255, 1
	s_nop 4
	s_load_dword s2, s[0:1], 0x100
	s_load_dwordx2 s[4:5], s[0:1], 0xf0
	s_getreg_b32 s3, hwreg(HW_REG_XCC_ID, 0, 4)
	s_and_b32 s3, s3, 15
	s_lshl_b32 s3, s3, 8
	v_and_b32_e32 v2, 7, v218
	v_lshlrev_b32_e32 v2, 2, v2
	s_waitcnt lgkmcnt(0)
	s_add_u32 s4, s4, 0x14000
	s_addc_u32 s5, s5, 0
	s_nop 1
	global_load_dword v3, v2, s[4:5] offset:64 sc1
	global_load_dword v4, v2, s[4:5] offset:128 sc1
	s_waitcnt vmcnt(0)
	v_add_u32_e32 v4, v3, v4
	v_cmp_ne_u32_e32 vcc, 17, v4
	v_add_u32_e32 v3, -1, v3
	v_lshlrev_b32_e64 v3, v3, 1
	s_nop 1
	v_readlane_b32 s1, v3, 0
	v_readlane_b32 s0, v3, 1
	s_nop 1
	s_or_b32 s1, s1, s0
	v_readlane_b32 s0, v3, 2
	s_nop 1
	s_or_b32 s1, s1, s0
	v_readlane_b32 s0, v3, 3
	s_nop 1
	s_or_b32 s1, s1, s0
	v_readlane_b32 s0, v3, 4
	s_nop 1
	s_or_b32 s1, s1, s0
	v_readlane_b32 s0, v3, 5
	s_nop 1
	s_or_b32 s1, s1, s0
	v_readlane_b32 s0, v3, 6
	s_nop 1
	s_or_b32 s1, s1, s0
	v_readlane_b32 s0, v3, 7
	s_nop 1
	s_or_b32 s1, s1, s0
	s_bcnt1_i32_b32 s0, s1
	s_add_u32 s4, s4, s3
	s_addc_u32 s5, s5, 0
	s_add_u32 s4, s4, 0x100
	s_addc_u32 s5, s5, 0
	s_cmp_eq_u32 s0, 8
	s_cselect_b32 s1, 32, 0
	s_cmp_eq_u64 vcc, 0
	s_cselect_b32 s1, s1, 0
	s_cmpk_eq_u32 s2, 0x100
	s_cselect_b32 s1, s1, 0
	v_writelane_b32 v255, s1, 40
	v_writelane_b32 v255, s4, 41
	v_writelane_b32 v255, s5, 42
	s_sub_u32 s4, s4, s3
	s_subb_u32 s5, s5, 0
	s_sub_u32 s4, s4, 0xe0
	s_subb_u32 s5, s5, 0
	v_writelane_b32 v255, s4, 45
	v_writelane_b32 v255, s5, 46
	s_mov_b32 s4, 0
	v_writelane_b32 v255, s4, 43
	v_writelane_b32 v255, s4, 44
	s_load_dword s0, s[78:79], 0x108
	s_add_i32 s2, 0, 0x1c800
	v_writelane_b32 v255, s2, 2
	s_add_i32 s2, 0, 0x1e020
	v_writelane_b32 v255, s2, 3
	s_add_i32 s2, 0, 0x1e820
	v_writelane_b32 v255, s2, 4
	s_add_i32 s2, 0, 0x1e3a0
	s_mul_i32 s1, s77, s76
	v_writelane_b32 v255, s2, 5
	s_waitcnt lgkmcnt(0)
	s_mul_i32 s77, s1, s0
	v_writelane_b32 v255, s97, 6
	s_add_i32 s84, 0, 0x23fc0
	v_writelane_b32 v255, s77, 7
	s_add_i32 s85, 0, 0x23fc4
	v_writelane_b32 v255, s84, 8
	s_mov_b32 s81, 0
	s_mov_b64 s[12:13], -1
	s_movk_i32 s68, 0xb00
	s_movk_i32 s0, 0x2000
	s_mov_b32 s69, 0x1fffe0
	s_movk_i32 s70, 0x161
	s_mov_b32 s71, 0x10000
	v_mov_b32_e32 v0, 0
	s_mov_b64 s[72:73], 0x40000
	s_movk_i32 s1, 0x3c0
	s_mov_b32 s74, 0x18000
	s_mov_b64 s[94:95], 0x80
	s_mov_b32 s75, 0x8000
	s_movk_i32 s82, 0x80
	v_mov_b32_e32 v219, 0x358637bd
	s_mov_b32 s86, 0x800000
	s_movk_i32 s83, 0x1600
	s_mov_b64 s[90:91], 0x10000
	v_mov_b32_e32 v254, 0x2000
	v_mov_b32_e32 v225, 0x13000
	v_mov_b32_e32 v253, 1
	s_mov_b32 s87, 0x40000
	s_mov_b32 s92, 0x48000
	s_mov_b32 s93, 0x50000
	s_movk_i32 s33, 0x1000
	s_movk_i32 s88, 0x3000
	s_movk_i32 s89, 0x101
	v_mov_b32_e32 v224, 0x260
	v_mov_b64_e32 v[200:201], 0x200
	v_mov_b64_e32 v[202:203], 0x1ff
	v_mov_b32_e32 v226, 0x80
	v_mov_b32_e32 v227, 0xfe0
	s_mov_b32 s6, 0
	s_mov_b32 s96, 0x3e38aa3b
	v_writelane_b32 v255, s85, 9
	s_branch .LBB0_102

.LBB0_263:
	s_waitcnt vmcnt(0)
	v_mov_b32_e32 v1, v218
	s_waitcnt vmcnt(0) lgkmcnt(0)
	s_barrier
	s_nop 0
	v_readlane_b32 s100, v255, 40
	s_nop 3
	s_cmp_eq_u32 s100, 0
	s_cbranch_scc1 .Lsp_noF_2
	v_readlane_b32 s100, v255, 44
	s_nop 3
	s_add_i32 s100, s100, 1
	v_writelane_b32 v255, s100, 44
	s_mov_b32 s100, 1
	s_nop 0
	v_writelane_b32 v255, s100, 43
.Lsp_noF_2:
	v_cmp_eq_u32_e32 vcc, 0, v1
	s_and_saveexec_b64 s[2:3], vcc
	s_cbranch_execz .LBB0_315
	v_readlane_b32 s100, v255, 40
	s_nop 3
	s_cmp_eq_u32 s100, 0
	s_cbranch_scc1 .Lfb_slow_2
	v_readlane_b32 s100, v255, 41
	v_readlane_b32 s101, v255, 42
	v_mov_b32_e32 v2, 0
	v_mov_b32_e32 v3, 1
	v_mov_b32_e32 v4, 1
	s_nop 2
	global_atomic_add v3, v2, v3, s[100:101] sc0
	s_waitcnt vmcnt(0)
	v_readfirstlane_b32 vcc_hi, v3
	s_nop 3
	s_lshr_b32 vcc_lo, vcc_hi, 5
	s_add_i32 vcc_hi, vcc_hi, 1
	s_and_b32 vcc_hi, vcc_hi, 31
	s_cmp_lg_u32 vcc_hi, 0
	s_cbranch_scc1 .Lfb_spin_2
	global_atomic_add v2, v4, s[100:101] offset:128
	buffer_wbl2 sc1
	s_waitcnt vmcnt(0)
	v_readlane_b32 s100, v255, 45
	v_readlane_b32 s101, v255, 46
	s_nop 4
	global_atomic_add v2, v4, s[100:101]
	s_branch .Lfb_done_2

.Lfb_slow_2:
	v_mov_b32_e32 v1, s84
	s_getreg_b32 s4, hwreg(HW_REG_XCC_ID, 0, 4)
	s_waitcnt vmcnt(0) expcnt(0) lgkmcnt(0)
	ds_read_b32 v3, v1
	v_mov_b32_e32 v1, s85
	ds_read_b32 v2, v1
	s_and_b32 s48, s4, 15
	s_waitcnt lgkmcnt(1)
	v_cmp_ne_u32_e32 vcc, 0, v3
	s_cbranch_vccnz .LBB0_279
	s_add_u32 s4, s10, 0x10200
	s_addc_u32 s5, s11, 0
	s_add_u32 s6, s10, 0x10400
	s_addc_u32 s7, s11, 0
	s_add_u32 s8, s10, 0x10500
	s_addc_u32 s9, s11, 0
	s_add_u32 s12, s10, 0x10600
	s_addc_u32 s13, s11, 0
	s_add_u32 s14, s10, 0x10700
	s_addc_u32 s15, s11, 0
	s_add_u32 s16, s10, 0x10800
	s_addc_u32 s17, s11, 0
	s_add_u32 s18, s10, 0x10900
	s_addc_u32 s19, s11, 0
	s_add_u32 s20, s10, 0x10a00
	s_addc_u32 s21, s11, 0
	s_add_u32 s22, s10, 0x10b00
	s_addc_u32 s23, s11, 0
	s_add_u32 s24, s10, 0x10c00
	s_addc_u32 s25, s11, 0
	s_add_u32 s26, s10, 0x10d00
	s_addc_u32 s27, s11, 0
	s_add_u32 s28, s10, 0x10e00
	s_addc_u32 s29, s11, 0
	s_add_u32 s30, s10, 0x10f00
	s_addc_u32 s31, s11, 0
	s_add_u32 s34, s10, 0x11000
	s_addc_u32 s35, s11, 0
	s_add_u32 s36, s10, 0x11100
	s_addc_u32 s37, s11, 0
	s_add_u32 s38, s10, 0x11200
	s_addc_u32 s39, s11, 0
	s_add_u32 s40, s10, 0x11300
	s_addc_u32 s41, s11, 0
	s_mov_b32 s49, 1
	s_branch .LBB0_267

.LBB0_329:
	v_mov_b32_e32 v167, v218
	s_lshl_b32 s5, s4, 8
	v_and_b32_e32 v164, 15, v167
	v_or_b32_e32 v142, s58, v164
	v_add_u32_e32 v142, s5, v142
	v_ashrrev_i32_e32 v143, 31, v142
	v_lshl_add_u64 v[158:159], v[142:143], 3, s[12:13]
	global_load_dwordx2 v[144:145], v[158:159], off
	global_load_dwordx2 v[176:177], v[158:159], off offset:128
	global_load_dwordx2 v[178:179], v[158:159], off offset:256
	global_load_dwordx2 v[180:181], v[158:159], off offset:384
	global_load_dwordx2 v[182:183], v[158:159], off offset:1024
	global_load_dwordx2 v[184:185], v[158:159], off offset:1152
	global_load_dwordx2 v[186:187], v[158:159], off offset:1280
	global_load_dwordx2 v[188:189], v[158:159], off offset:1408
	v_readlane_b32 s100, v255, 43
	s_nop 3
	s_cmp_eq_u32 s100, 0
	s_cbranch_scc1 .Lsw_skip_inproj
	v_readfirstlane_b32 s101, v218
	s_nop 3
	s_lshr_b32 s101, s101, 6
	s_cmp_lg_u32 s101, 0
	s_cbranch_scc1 .Lsw_join_inproj
	v_readlane_b32 s101, v255, 45
	s_nop 3
	v_mov_b32_e32 v190, s101
	v_readlane_b32 s101, v255, 46
	s_nop 3
	v_mov_b32_e32 v191, s101
	v_readlane_b32 s100, v255, 44
	s_nop 3
	s_lshl_b32 s100, s100, 3
.Lsw_spin_inproj:
	global_load_dword v192, v[190:191], off sc1
	s_waitcnt vmcnt(0)
	v_readfirstlane_b32 s101, v192
	s_nop 3
	s_cmp_ge_u32 s101, s100
	s_cbranch_scc1 .Lsw_join_inproj
	s_sleep 1
	s_branch .Lsw_spin_inproj
.Lsw_join_inproj:
	s_barrier
	s_mov_b32 s100, 0
	s_nop 0
	v_writelane_b32 v255, s100, 43
.Lsw_skip_inproj:
	v_bfe_u32 v165, v167, 4, 2
	v_lshlrev_b32_e32 v168, 3, v165
	v_or_b32_e32 v169, s59, v168
	s_mov_b64 s[28:29], -1
	s_cmp_gt_i32 s26, 1
	s_waitcnt vmcnt(0)
	v_ffbh_u32_e32 v146, v145
	v_min_u32_e32 v146, 32, v146
	v_lshlrev_b64 v[144:145], v146, v[144:145]
	v_min_u32_e32 v144, 1, v144
	v_or_b32_e32 v144, v145, v144
	v_cvt_f32_u32_e32 v144, v144
	v_sub_u32_e32 v145, 32, v146
	v_ldexp_f32 v144, v144, v145
	v_fmamk_f32 v144, v144, 0x31800000, v219
	v_cmp_gt_f32_e32 vcc, s86, v144
	v_mul_f32_e32 v145, 0x4b800000, v144
	s_nop 0
	v_cndmask_b32_e32 v144, v144, v145, vcc
	v_rsq_f32_e32 v144, v144
	s_nop 0
	v_mul_f32_e32 v145, 0x45800000, v144
	v_cndmask_b32_e32 v146, v144, v145, vcc
	v_pk_mul_f32 v[128:129], v[128:129], v[146:147] op_sel_hi:[1,0]
	v_pk_mul_f32 v[126:127], v[126:127], v[146:147] op_sel_hi:[1,0]
	v_pk_mul_f32 v[124:125], v[124:125], v[146:147] op_sel_hi:[1,0]
	v_pk_mul_f32 v[122:123], v[122:123], v[146:147] op_sel_hi:[1,0]
	v_pk_mul_f32 v[120:121], v[120:121], v[146:147] op_sel_hi:[1,0]
	v_pk_mul_f32 v[144:145], v[118:119], v[146:147] op_sel_hi:[1,0]
	v_pk_mul_f32 v[116:117], v[116:117], v[146:147] op_sel_hi:[1,0]
	v_pk_mul_f32 v[118:119], v[114:115], v[146:147] op_sel_hi:[1,0]
	v_mov_b64_e32 v[146:147], v[176:177]
	v_or_b32_e32 v114, 16, v142
	v_ashrrev_i32_e32 v115, 31, v114
	s_nop 0
	v_ffbh_u32_e32 v148, v147
	v_min_u32_e32 v148, 32, v148
	v_lshlrev_b64 v[146:147], v148, v[146:147]
	v_min_u32_e32 v146, 1, v146
	v_or_b32_e32 v146, v147, v146
	v_cvt_f32_u32_e32 v146, v146
	v_sub_u32_e32 v147, 32, v148
	v_ldexp_f32 v146, v146, v147
	v_fmamk_f32 v146, v146, 0x31800000, v219
	v_cmp_gt_f32_e32 vcc, s86, v146
	v_mul_f32_e32 v147, 0x4b800000, v146
	s_nop 0
	v_cndmask_b32_e32 v146, v146, v147, vcc
	v_rsq_f32_e32 v146, v146
	s_nop 0
	v_mul_f32_e32 v147, 0x45800000, v146
	v_cndmask_b32_e32 v148, v146, v147, vcc
	v_pk_mul_f32 v[112:113], v[112:113], v[148:149] op_sel_hi:[1,0]
	v_pk_mul_f32 v[110:111], v[110:111], v[148:149] op_sel_hi:[1,0]
	v_pk_mul_f32 v[108:109], v[108:109], v[148:149] op_sel_hi:[1,0]
	v_pk_mul_f32 v[106:107], v[106:107], v[148:149] op_sel_hi:[1,0]
	v_pk_mul_f32 v[104:105], v[104:105], v[148:149] op_sel_hi:[1,0]
	v_pk_mul_f32 v[146:147], v[102:103], v[148:149] op_sel_hi:[1,0]
	v_pk_mul_f32 v[100:101], v[100:101], v[148:149] op_sel_hi:[1,0]
	v_pk_mul_f32 v[102:103], v[98:99], v[148:149] op_sel_hi:[1,0]
	v_mov_b64_e32 v[148:149], v[178:179]
	v_or_b32_e32 v98, 32, v142
	v_ashrrev_i32_e32 v99, 31, v98
	s_nop 0
	v_ffbh_u32_e32 v150, v149
	v_min_u32_e32 v150, 32, v150
	v_lshlrev_b64 v[148:149], v150, v[148:149]
	v_min_u32_e32 v148, 1, v148
	v_or_b32_e32 v148, v149, v148
	v_cvt_f32_u32_e32 v148, v148
	v_sub_u32_e32 v149, 32, v150
	v_ldexp_f32 v148, v148, v149
	v_fmamk_f32 v148, v148, 0x31800000, v219
	v_cmp_gt_f32_e32 vcc, s86, v148
	v_mul_f32_e32 v149, 0x4b800000, v148
	s_nop 0
	v_cndmask_b32_e32 v148, v148, v149, vcc
	v_rsq_f32_e32 v148, v148
	s_nop 0
	v_mul_f32_e32 v149, 0x45800000, v148
	v_cndmask_b32_e32 v150, v148, v149, vcc
	v_pk_mul_f32 v[96:97], v[96:97], v[150:151] op_sel_hi:[1,0]
	v_pk_mul_f32 v[94:95], v[94:95], v[150:151] op_sel_hi:[1,0]
	v_pk_mul_f32 v[92:93], v[92:93], v[150:151] op_sel_hi:[1,0]
	v_pk_mul_f32 v[90:91], v[90:91], v[150:151] op_sel_hi:[1,0]
	v_pk_mul_f32 v[88:89], v[88:89], v[150:151] op_sel_hi:[1,0]
	v_pk_mul_f32 v[148:149], v[86:87], v[150:151] op_sel_hi:[1,0]
	v_pk_mul_f32 v[84:85], v[84:85], v[150:151] op_sel_hi:[1,0]
	v_pk_mul_f32 v[86:87], v[82:83], v[150:151] op_sel_hi:[1,0]
	v_mov_b64_e32 v[150:151], v[180:181]
	v_or_b32_e32 v82, 48, v142
	v_ashrrev_i32_e32 v83, 31, v82
	s_nop 0
	v_ffbh_u32_e32 v152, v151
	v_min_u32_e32 v152, 32, v152
	v_lshlrev_b64 v[150:151], v152, v[150:151]
	v_min_u32_e32 v150, 1, v150
	v_or_b32_e32 v150, v151, v150
	v_cvt_f32_u32_e32 v150, v150
	v_sub_u32_e32 v151, 32, v152
	v_ldexp_f32 v150, v150, v151
	v_fmamk_f32 v150, v150, 0x31800000, v219
	v_cmp_gt_f32_e32 vcc, s86, v150
	v_mul_f32_e32 v151, 0x4b800000, v150
	s_nop 0
	v_cndmask_b32_e32 v150, v150, v151, vcc
	v_rsq_f32_e32 v150, v150
	s_nop 0
	v_mul_f32_e32 v151, 0x45800000, v150
	v_cndmask_b32_e32 v152, v150, v151, vcc
	v_pk_mul_f32 v[80:81], v[80:81], v[152:153] op_sel_hi:[1,0]
	v_pk_mul_f32 v[78:79], v[78:79], v[152:153] op_sel_hi:[1,0]
	v_pk_mul_f32 v[76:77], v[76:77], v[152:153] op_sel_hi:[1,0]
	v_pk_mul_f32 v[74:75], v[74:75], v[152:153] op_sel_hi:[1,0]
	v_pk_mul_f32 v[72:73], v[72:73], v[152:153] op_sel_hi:[1,0]
	v_pk_mul_f32 v[150:151], v[70:71], v[152:153] op_sel_hi:[1,0]
	v_pk_mul_f32 v[68:69], v[68:69], v[152:153] op_sel_hi:[1,0]
	v_pk_mul_f32 v[70:71], v[66:67], v[152:153] op_sel_hi:[1,0]
	v_mov_b64_e32 v[152:153], v[182:183]
	v_add_u32_e32 v66, 0x80, v142
	v_ashrrev_i32_e32 v67, 31, v66
	s_nop 0
	v_ffbh_u32_e32 v154, v153
	v_min_u32_e32 v154, 32, v154
	v_lshlrev_b64 v[152:153], v154, v[152:153]
	v_min_u32_e32 v152, 1, v152
	v_or_b32_e32 v152, v153, v152
	v_cvt_f32_u32_e32 v152, v152
	v_sub_u32_e32 v153, 32, v154
	v_ldexp_f32 v152, v152, v153
	v_fmamk_f32 v152, v152, 0x31800000, v219
	v_cmp_gt_f32_e32 vcc, s86, v152
	v_mul_f32_e32 v153, 0x4b800000, v152
	s_nop 0
	v_cndmask_b32_e32 v152, v152, v153, vcc
	v_rsq_f32_e32 v152, v152
	s_nop 0
	v_mul_f32_e32 v153, 0x45800000, v152
	v_cndmask_b32_e32 v154, v152, v153, vcc
	v_pk_mul_f32 v[64:65], v[64:65], v[154:155] op_sel_hi:[1,0]
	v_pk_mul_f32 v[62:63], v[62:63], v[154:155] op_sel_hi:[1,0]
	v_pk_mul_f32 v[60:61], v[60:61], v[154:155] op_sel_hi:[1,0]
	v_pk_mul_f32 v[58:59], v[58:59], v[154:155] op_sel_hi:[1,0]
	v_pk_mul_f32 v[56:57], v[56:57], v[154:155] op_sel_hi:[1,0]
	v_pk_mul_f32 v[152:153], v[54:55], v[154:155] op_sel_hi:[1,0]
	v_pk_mul_f32 v[52:53], v[52:53], v[154:155] op_sel_hi:[1,0]
	v_pk_mul_f32 v[54:55], v[50:51], v[154:155] op_sel_hi:[1,0]
	v_mov_b64_e32 v[154:155], v[184:185]
	v_add_u32_e32 v50, 0x90, v142
	v_ashrrev_i32_e32 v51, 31, v50
	s_nop 0
	v_ffbh_u32_e32 v156, v155
	v_min_u32_e32 v156, 32, v156
	v_lshlrev_b64 v[154:155], v156, v[154:155]
	v_min_u32_e32 v154, 1, v154
	v_or_b32_e32 v154, v155, v154
	v_cvt_f32_u32_e32 v154, v154
	v_sub_u32_e32 v155, 32, v156
	v_ldexp_f32 v154, v154, v155
	v_fmamk_f32 v154, v154, 0x31800000, v219
	v_cmp_gt_f32_e32 vcc, s86, v154
	v_mul_f32_e32 v155, 0x4b800000, v154
	s_nop 0
	v_cndmask_b32_e32 v154, v154, v155, vcc
	v_rsq_f32_e32 v154, v154
	s_nop 0
	v_mul_f32_e32 v155, 0x45800000, v154
	v_cndmask_b32_e32 v156, v154, v155, vcc
	v_pk_mul_f32 v[48:49], v[48:49], v[156:157] op_sel_hi:[1,0]
	v_pk_mul_f32 v[46:47], v[46:47], v[156:157] op_sel_hi:[1,0]
	v_pk_mul_f32 v[44:45], v[44:45], v[156:157] op_sel_hi:[1,0]
	v_pk_mul_f32 v[42:43], v[42:43], v[156:157] op_sel_hi:[1,0]
	v_pk_mul_f32 v[40:41], v[40:41], v[156:157] op_sel_hi:[1,0]
	v_pk_mul_f32 v[154:155], v[38:39], v[156:157] op_sel_hi:[1,0]
	v_pk_mul_f32 v[36:37], v[36:37], v[156:157] op_sel_hi:[1,0]
	v_pk_mul_f32 v[38:39], v[34:35], v[156:157] op_sel_hi:[1,0]
	v_mov_b64_e32 v[156:157], v[186:187]
	v_add_u32_e32 v34, 0xa0, v142
	v_mov_b64_e32 v[158:159], v[188:189]
	v_ashrrev_i32_e32 v35, 31, v34
	s_nop 0
	v_ffbh_u32_e32 v160, v157
	v_min_u32_e32 v160, 32, v160
	v_lshlrev_b64 v[156:157], v160, v[156:157]
	v_min_u32_e32 v156, 1, v156
	v_or_b32_e32 v156, v157, v156
	v_cvt_f32_u32_e32 v156, v156
	v_sub_u32_e32 v157, 32, v160
	v_ldexp_f32 v156, v156, v157
	v_fmamk_f32 v156, v156, 0x31800000, v219
	v_cmp_gt_f32_e32 vcc, s86, v156
	v_mul_f32_e32 v157, 0x4b800000, v156
	s_nop 0
	v_cndmask_b32_e32 v156, v156, v157, vcc
	v_rsq_f32_e32 v156, v156
	s_nop 0
	v_mul_f32_e32 v157, 0x45800000, v156
	v_cndmask_b32_e32 v160, v156, v157, vcc
	v_pk_mul_f32 v[32:33], v[32:33], v[160:161] op_sel_hi:[1,0]
	v_pk_mul_f32 v[30:31], v[30:31], v[160:161] op_sel_hi:[1,0]
	v_pk_mul_f32 v[28:29], v[28:29], v[160:161] op_sel_hi:[1,0]
	v_pk_mul_f32 v[26:27], v[26:27], v[160:161] op_sel_hi:[1,0]
	v_pk_mul_f32 v[24:25], v[24:25], v[160:161] op_sel_hi:[1,0]
	v_pk_mul_f32 v[156:157], v[22:23], v[160:161] op_sel_hi:[1,0]
	v_pk_mul_f32 v[20:21], v[20:21], v[160:161] op_sel_hi:[1,0]
	v_pk_mul_f32 v[22:23], v[18:19], v[160:161] op_sel_hi:[1,0]
	s_nop 0
	v_ffbh_u32_e32 v160, v159
	v_min_u32_e32 v160, 32, v160
	v_lshlrev_b64 v[158:159], v160, v[158:159]
	v_min_u32_e32 v158, 1, v158
	v_or_b32_e32 v158, v159, v158
	v_cvt_f32_u32_e32 v158, v158
	v_sub_u32_e32 v159, 32, v160
	v_add_u32_e32 v18, 0xb0, v142
	v_ashrrev_i32_e32 v19, 31, v18
	v_ldexp_f32 v158, v158, v159
	v_fmamk_f32 v158, v158, 0x31800000, v219
	v_cmp_gt_f32_e32 vcc, s86, v158
	v_mul_f32_e32 v159, 0x4b800000, v158
	s_nop 0
	v_cndmask_b32_e32 v158, v158, v159, vcc
	v_rsq_f32_e32 v158, v158
	s_nop 0
	v_mul_f32_e32 v159, 0x45800000, v158
	v_cndmask_b32_e32 v158, v158, v159, vcc
	v_pk_mul_f32 v[16:17], v[16:17], v[158:159] op_sel_hi:[1,0]
	v_pk_mul_f32 v[14:15], v[14:15], v[158:159] op_sel_hi:[1,0]
	v_pk_mul_f32 v[12:13], v[12:13], v[158:159] op_sel_hi:[1,0]
	v_pk_mul_f32 v[10:11], v[10:11], v[158:159] op_sel_hi:[1,0]
	v_pk_mul_f32 v[8:9], v[8:9], v[158:159] op_sel_hi:[1,0]
	v_pk_mul_f32 v[6:7], v[6:7], v[158:159] op_sel_hi:[1,0]
	v_pk_mul_f32 v[4:5], v[4:5], v[158:159] op_sel_hi:[1,0]
	v_pk_mul_f32 v[2:3], v[2:3], v[158:159] op_sel_hi:[1,0]
	s_cbranch_scc0 .LBB0_339
	s_cmp_eq_u32 s26, 4
	s_cselect_b64 s[28:29], -1, 0
	s_cmp_lg_u32 s26, 4
	s_cselect_b64 s[30:31], -1, 0
	s_and_b32 s19, s26, 0x7ffffffe
	s_cmp_lg_u32 s19, 6
	s_cselect_b64 s[34:35], -1, 0
	s_and_b64 s[34:35], s[30:31], s[34:35]
	s_mov_b64 s[30:31], -1
	s_and_b64 vcc, exec, s[34:35]
	s_cbranch_vccz .LBB0_336
	s_cmp_lt_u32 s26, 8
	s_cbranch_scc0 .LBB0_333
	s_cmp_eq_u32 s26, 3
	s_movk_i32 s19, 0x300
	s_cselect_b32 s19, 0x200, s19
	s_cmp_lg_u32 s26, 2
	v_lshlrev_b64 v[158:159], 11, v[142:143]
	s_cselect_b32 s19, s19, 0x100
	v_lshl_add_u64 v[158:159], s[10:11], 0, v[158:159]
	s_lshl_b32 s80, s19, 1
	v_lshl_add_u64 v[158:159], v[158:159], 0, s[80:81]
	v_lshlrev_b32_e32 v162, 1, v169
	v_mov_b32_e32 v163, v0
	v_lshl_add_u64 v[170:171], v[158:159], 0, v[162:163]
	v_cvt_pk_bf16_f32 v158, v126, v127
	v_cvt_pk_bf16_f32 v159, v128, v129
	v_cvt_pk_bf16_f32 v160, v122, v123
	v_cvt_pk_bf16_f32 v161, v124, v125
	global_store_dwordx4 v[170:171], v[158:161], off
	s_mov_b64 s[30:31], 0
	s_nop 0
	v_cvt_pk_bf16_f32 v158, v144, v145
	v_cvt_pk_bf16_f32 v159, v120, v121
	v_cvt_pk_bf16_f32 v160, v118, v119
	v_cvt_pk_bf16_f32 v161, v116, v117
	global_store_dwordx4 v[170:171], v[158:161], off offset:256
	s_nop 1
	v_lshlrev_b64 v[158:159], 11, v[114:115]
	v_lshl_add_u64 v[158:159], s[10:11], 0, v[158:159]
	v_lshl_add_u64 v[158:159], v[158:159], 0, s[80:81]
	v_lshl_add_u64 v[170:171], v[158:159], 0, v[162:163]
	v_cvt_pk_bf16_f32 v158, v110, v111
	v_cvt_pk_bf16_f32 v159, v112, v113
	v_cvt_pk_bf16_f32 v160, v106, v107
	v_cvt_pk_bf16_f32 v161, v108, v109
	global_store_dwordx4 v[170:171], v[158:161], off
	s_nop 1
	v_cvt_pk_bf16_f32 v158, v146, v147
	v_cvt_pk_bf16_f32 v159, v104, v105
	v_cvt_pk_bf16_f32 v160, v102, v103
	v_cvt_pk_bf16_f32 v161, v100, v101
	global_store_dwordx4 v[170:171], v[158:161], off offset:256
	s_nop 1
	v_lshlrev_b64 v[158:159], 11, v[98:99]
	v_lshl_add_u64 v[158:159], s[10:11], 0, v[158:159]
	v_lshl_add_u64 v[158:159], v[158:159], 0, s[80:81]
	v_lshl_add_u64 v[170:171], v[158:159], 0, v[162:163]
	v_cvt_pk_bf16_f32 v158, v94, v95
	v_cvt_pk_bf16_f32 v159, v96, v97
	v_cvt_pk_bf16_f32 v160, v90, v91
	v_cvt_pk_bf16_f32 v161, v92, v93
	global_store_dwordx4 v[170:171], v[158:161], off
	s_nop 1
	v_cvt_pk_bf16_f32 v158, v148, v149
	v_cvt_pk_bf16_f32 v159, v88, v89
	v_cvt_pk_bf16_f32 v160, v86, v87
	v_cvt_pk_bf16_f32 v161, v84, v85
	global_store_dwordx4 v[170:171], v[158:161], off offset:256
	s_nop 1
	v_lshlrev_b64 v[158:159], 11, v[82:83]
	v_lshl_add_u64 v[158:159], s[10:11], 0, v[158:159]
	v_lshl_add_u64 v[158:159], v[158:159], 0, s[80:81]
	v_lshl_add_u64 v[170:171], v[158:159], 0, v[162:163]
	v_cvt_pk_bf16_f32 v158, v78, v79
	v_cvt_pk_bf16_f32 v159, v80, v81
	v_cvt_pk_bf16_f32 v160, v74, v75
	v_cvt_pk_bf16_f32 v161, v76, v77
	global_store_dwordx4 v[170:171], v[158:161], off
	s_nop 1
	v_cvt_pk_bf16_f32 v158, v150, v151
	v_cvt_pk_bf16_f32 v159, v72, v73
	v_cvt_pk_bf16_f32 v160, v70, v71
	v_cvt_pk_bf16_f32 v161, v68, v69
	global_store_dwordx4 v[170:171], v[158:161], off offset:256
	s_nop 1
	v_lshlrev_b64 v[158:159], 11, v[66:67]
	v_lshl_add_u64 v[158:159], s[10:11], 0, v[158:159]
	v_lshl_add_u64 v[158:159], v[158:159], 0, s[80:81]
	v_lshl_add_u64 v[170:171], v[158:159], 0, v[162:163]
	v_cvt_pk_bf16_f32 v158, v62, v63
	v_cvt_pk_bf16_f32 v159, v64, v65
	v_cvt_pk_bf16_f32 v160, v58, v59
	v_cvt_pk_bf16_f32 v161, v60, v61
	global_store_dwordx4 v[170:171], v[158:161], off
	s_nop 1
	v_cvt_pk_bf16_f32 v158, v152, v153
	v_cvt_pk_bf16_f32 v159, v56, v57
	v_cvt_pk_bf16_f32 v160, v54, v55
	v_cvt_pk_bf16_f32 v161, v52, v53
	global_store_dwordx4 v[170:171], v[158:161], off offset:256
	s_nop 1
	v_lshlrev_b64 v[158:159], 11, v[50:51]
	v_lshl_add_u64 v[158:159], s[10:11], 0, v[158:159]
	v_lshl_add_u64 v[158:159], v[158:159], 0, s[80:81]
	v_lshl_add_u64 v[170:171], v[158:159], 0, v[162:163]
	v_cvt_pk_bf16_f32 v158, v46, v47
	v_cvt_pk_bf16_f32 v159, v48, v49
	v_cvt_pk_bf16_f32 v160, v42, v43
	v_cvt_pk_bf16_f32 v161, v44, v45
	global_store_dwordx4 v[170:171], v[158:161], off
	s_nop 1
	v_cvt_pk_bf16_f32 v158, v154, v155
	v_cvt_pk_bf16_f32 v159, v40, v41
	v_cvt_pk_bf16_f32 v160, v38, v39
	v_cvt_pk_bf16_f32 v161, v36, v37
	global_store_dwordx4 v[170:171], v[158:161], off offset:256
	s_nop 1
	v_lshlrev_b64 v[158:159], 11, v[34:35]
	v_lshl_add_u64 v[158:159], s[10:11], 0, v[158:159]
	v_lshl_add_u64 v[158:159], v[158:159], 0, s[80:81]
	v_lshl_add_u64 v[170:171], v[158:159], 0, v[162:163]
	v_cvt_pk_bf16_f32 v158, v30, v31
	v_cvt_pk_bf16_f32 v159, v32, v33
	v_cvt_pk_bf16_f32 v160, v26, v27
	v_cvt_pk_bf16_f32 v161, v28, v29
	global_store_dwordx4 v[170:171], v[158:161], off
	s_nop 1
	v_cvt_pk_bf16_f32 v158, v156, v157
	v_cvt_pk_bf16_f32 v159, v24, v25
	v_cvt_pk_bf16_f32 v160, v22, v23
	v_cvt_pk_bf16_f32 v161, v20, v21
	global_store_dwordx4 v[170:171], v[158:161], off offset:256
	s_nop 1
	v_lshlrev_b64 v[158:159], 11, v[18:19]
	v_lshl_add_u64 v[158:159], s[10:11], 0, v[158:159]
	v_lshl_add_u64 v[158:159], v[158:159], 0, s[80:81]
	v_lshl_add_u64 v[162:163], v[158:159], 0, v[162:163]
	v_cvt_pk_bf16_f32 v158, v14, v15
	v_cvt_pk_bf16_f32 v159, v16, v17
	v_cvt_pk_bf16_f32 v160, v10, v11
	v_cvt_pk_bf16_f32 v161, v12, v13
	global_store_dwordx4 v[162:163], v[158:161], off
	s_nop 1
	v_cvt_pk_bf16_f32 v158, v6, v7
	v_cvt_pk_bf16_f32 v159, v8, v9
	v_cvt_pk_bf16_f32 v160, v2, v3
	v_cvt_pk_bf16_f32 v161, v4, v5
	global_store_dwordx4 v[162:163], v[158:161], off offset:256

.LBB0_1119:
	s_waitcnt vmcnt(0)
	v_mov_b32_e32 v1, v218
	s_waitcnt lgkmcnt(0)
	s_barrier
	s_nop 0
	v_readlane_b32 s100, v255, 40
	s_nop 3
	s_cmp_eq_u32 s100, 0
	s_cbranch_scc1 .Lsp_noF_8
	v_readlane_b32 s100, v255, 44
	s_nop 3
	s_add_i32 s100, s100, 1
	v_writelane_b32 v255, s100, 44
	s_mov_b32 s100, 1
	s_nop 0
	v_writelane_b32 v255, s100, 43

.LBB0_1183:
	v_mov_b32_e32 v143, v218
	s_lshl_b32 s15, s22, 8
	s_add_i32 s15, s15, s45
	v_and_or_b32 v142, v143, 15, s15
	s_lshl_b32 s15, s23, 7
	v_lshrrev_b32_e32 v143, 1, v143
	v_and_or_b32 v143, v143, 24, s15
	v_or_b32_e32 v148, s46, v143
	v_ashrrev_i32_e32 v143, 31, v142
	v_lshl_add_u64 v[144:145], v[142:143], 3, s[10:11]
	global_load_dwordx2 v[146:147], v[144:145], off
	global_load_dwordx2 v[158:159], v[144:145], off offset:128
	global_load_dwordx2 v[160:161], v[144:145], off offset:256
	global_load_dwordx2 v[162:163], v[144:145], off offset:384
	global_load_dwordx2 v[164:165], v[144:145], off offset:1024
	global_load_dwordx2 v[166:167], v[144:145], off offset:1152
	global_load_dwordx2 v[168:169], v[144:145], off offset:1280
	global_load_dwordx2 v[170:171], v[144:145], off offset:1408
	v_readlane_b32 s100, v255, 43
	s_nop 3
	s_cmp_eq_u32 s100, 0
	s_cbranch_scc1 .Lsw_skip_ffn2up
	v_readfirstlane_b32 s101, v218
	s_nop 3
	s_lshr_b32 s101, s101, 6
	s_cmp_lg_u32 s101, 0
	s_cbranch_scc1 .Lsw_join_ffn2up
	v_readlane_b32 s101, v255, 45
	s_nop 3
	v_mov_b32_e32 v172, s101
	v_readlane_b32 s101, v255, 46
	s_nop 3
	v_mov_b32_e32 v173, s101
	v_readlane_b32 s100, v255, 44
	s_nop 3
	s_lshl_b32 s100, s100, 3
.Lsw_spin_ffn2up:
	global_load_dword v174, v[172:173], off sc1
	s_waitcnt vmcnt(0)
	v_readfirstlane_b32 s101, v174
	s_nop 3
	s_cmp_ge_u32 s101, s100
	s_cbranch_scc1 .Lsw_join_ffn2up
	s_sleep 1
	s_branch .Lsw_spin_ffn2up

.Lsw_skip_ffn2up:
	v_ashrrev_i32_e32 v149, 31, v148
	s_waitcnt vmcnt(0)
	v_ffbh_u32_e32 v143, v147
	v_min_u32_e32 v143, 32, v143
	v_lshlrev_b64 v[146:147], v143, v[146:147]
	v_min_u32_e32 v146, 1, v146
	v_or_b32_e32 v146, v147, v146
	v_cvt_f32_u32_e32 v146, v146
	v_sub_u32_e32 v143, 32, v143
	v_ldexp_f32 v143, v146, v143
	v_fmamk_f32 v143, v143, 0x31800000, v219
	v_cmp_gt_f32_e32 vcc, s86, v143
	v_mul_f32_e32 v146, 0x4b800000, v143
	s_nop 0
	v_cndmask_b32_e32 v143, v143, v146, vcc
	v_rsq_f32_e32 v143, v143
	s_nop 0
	v_mul_f32_e32 v146, 0x45800000, v143
	v_cndmask_b32_e32 v154, v143, v146, vcc
	v_pk_mul_f32 v[126:127], v[126:127], v[154:155] op_sel_hi:[1,0]
	v_pk_mul_f32 v[118:119], v[118:119], v[154:155] op_sel_hi:[1,0]
	v_mul_f32_e32 v143, 0xbfb8aa3b, v126
	v_exp_f32_e32 v143, v143
	v_pk_mul_f32 v[120:121], v[120:121], v[154:155] op_sel_hi:[1,0]
	v_pk_mul_f32 v[122:123], v[122:123], v[154:155] op_sel_hi:[1,0]
	v_pk_mul_f32 v[114:115], v[114:115], v[154:155] op_sel_hi:[1,0]
	v_add_f32_e32 v143, 1.0, v143
	v_rcp_f32_e32 v156, v143
	v_mul_f32_e32 v143, 0xbfb8aa3b, v127
	v_exp_f32_e32 v143, v143
	v_mov_b64_e32 v[146:147], s[8:9]
	v_pk_mul_f32 v[116:117], v[116:117], v[154:155] op_sel_hi:[1,0]
	v_mad_i64_i32 v[150:151], s[22:23], v142, s83, v[146:147]
	v_add_f32_e32 v143, 1.0, v143
	v_rcp_f32_e32 v157, v143
	s_nop 0
	v_pk_mul_f32 v[126:127], v[126:127], v[156:157]
	s_nop 0
	v_pk_mul_f32 v[118:119], v[118:119], v[126:127]
	v_pk_mul_f32 v[126:127], v[128:129], v[154:155] op_sel_hi:[1,0]
	v_cvt_pk_bf16_f32 v118, v118, v119
	v_mul_f32_e32 v128, 0xbfb8aa3b, v126
	v_mul_f32_e32 v129, 0xbfb8aa3b, v127
	v_exp_f32_e32 v128, v128
	v_exp_f32_e32 v129, v129
	v_add_f32_e32 v128, 1.0, v128
	v_add_f32_e32 v129, 1.0, v129
	v_rcp_f32_e32 v128, v128
	v_rcp_f32_e32 v129, v129
	s_nop 0
	v_pk_mul_f32 v[126:127], v[126:127], v[128:129]
	s_nop 0
	v_pk_mul_f32 v[120:121], v[120:121], v[126:127]
	v_mul_f32_e32 v126, 0xbfb8aa3b, v122
	v_mul_f32_e32 v127, 0xbfb8aa3b, v123
	v_exp_f32_e32 v126, v126
	v_exp_f32_e32 v127, v127
	v_cvt_pk_bf16_f32 v119, v120, v121
	v_add_f32_e32 v126, 1.0, v126
	v_add_f32_e32 v127, 1.0, v127
	v_rcp_f32_e32 v126, v126
	v_rcp_f32_e32 v127, v127
	s_nop 0
	v_pk_mul_f32 v[122:123], v[122:123], v[126:127]
	s_nop 0
	v_pk_mul_f32 v[122:123], v[114:115], v[122:123]
	v_pk_mul_f32 v[114:115], v[124:125], v[154:155] op_sel_hi:[1,0]
	v_cvt_pk_bf16_f32 v120, v122, v123
	v_mul_f32_e32 v124, 0xbfb8aa3b, v114
	v_mul_f32_e32 v125, 0xbfb8aa3b, v115
	v_exp_f32_e32 v124, v124
	v_exp_f32_e32 v125, v125
	v_add_f32_e32 v124, 1.0, v124
	v_add_f32_e32 v125, 1.0, v125
	v_rcp_f32_e32 v124, v124
	v_rcp_f32_e32 v125, v125
	s_nop 0
	v_pk_mul_f32 v[114:115], v[114:115], v[124:125]
	s_nop 0
	v_pk_mul_f32 v[116:117], v[116:117], v[114:115]
	v_lshlrev_b64 v[114:115], 1, v[148:149]
	v_lshl_add_u64 v[124:125], v[150:151], 0, v[114:115]
	v_cvt_pk_bf16_f32 v121, v116, v117
	global_store_dwordx4 v[124:125], v[118:121], off
	v_mov_b64_e32 v[116:117], v[158:159]
	s_nop 0
	v_or_b32_e32 v119, 16, v142
	s_nop 0
	v_ffbh_u32_e32 v118, v117
	v_min_u32_e32 v118, 32, v118
	v_lshlrev_b64 v[116:117], v118, v[116:117]
	v_min_u32_e32 v116, 1, v116
	v_or_b32_e32 v116, v117, v116
	v_cvt_f32_u32_e32 v116, v116
	v_sub_u32_e32 v117, 32, v118
	v_ldexp_f32 v116, v116, v117
	v_fmamk_f32 v116, v116, 0x31800000, v219
	v_cmp_gt_f32_e32 vcc, s86, v116
	v_mul_f32_e32 v117, 0x4b800000, v116
	s_nop 0
	v_cndmask_b32_e32 v116, v116, v117, vcc
	v_rsq_f32_e32 v116, v116
	s_nop 0
	v_mul_f32_e32 v117, 0x45800000, v116
	v_cndmask_b32_e32 v118, v116, v117, vcc
	v_pk_mul_f32 v[110:111], v[110:111], v[118:119] op_sel_hi:[1,0]
	v_mad_i64_i32 v[116:117], s[22:23], v119, s83, v[146:147]
	v_mul_f32_e32 v119, 0xbfb8aa3b, v110
	v_exp_f32_e32 v119, v119
	s_nop 0
	v_add_f32_e32 v119, 1.0, v119
	v_rcp_f32_e32 v120, v119
	v_pk_mul_f32 v[102:103], v[102:103], v[118:119] op_sel_hi:[1,0]
	v_mul_f32_e32 v119, 0xbfb8aa3b, v111
	v_exp_f32_e32 v119, v119
	s_nop 0
	v_add_f32_e32 v119, 1.0, v119
	v_rcp_f32_e32 v121, v119
	v_pk_mul_f32 v[104:105], v[104:105], v[118:119] op_sel_hi:[1,0]
	v_pk_mul_f32 v[106:107], v[106:107], v[118:119] op_sel_hi:[1,0]
	v_pk_mul_f32 v[98:99], v[98:99], v[118:119] op_sel_hi:[1,0]
	v_pk_mul_f32 v[110:111], v[110:111], v[120:121]
	v_pk_mul_f32 v[100:101], v[100:101], v[118:119] op_sel_hi:[1,0]
	v_pk_mul_f32 v[102:103], v[102:103], v[110:111]
	v_pk_mul_f32 v[110:111], v[112:113], v[118:119] op_sel_hi:[1,0]
	v_cvt_pk_bf16_f32 v102, v102, v103
	v_mul_f32_e32 v112, 0xbfb8aa3b, v110
	v_mul_f32_e32 v113, 0xbfb8aa3b, v111
	v_exp_f32_e32 v112, v112
	v_exp_f32_e32 v113, v113
	v_add_f32_e32 v112, 1.0, v112
	v_add_f32_e32 v113, 1.0, v113
	v_rcp_f32_e32 v112, v112
	v_rcp_f32_e32 v113, v113
	s_nop 0
	v_pk_mul_f32 v[110:111], v[110:111], v[112:113]
	s_nop 0
	v_pk_mul_f32 v[104:105], v[104:105], v[110:111]
	v_mul_f32_e32 v110, 0xbfb8aa3b, v106
	v_mul_f32_e32 v111, 0xbfb8aa3b, v107
	v_exp_f32_e32 v110, v110
	v_exp_f32_e32 v111, v111
	v_cvt_pk_bf16_f32 v103, v104, v105
	v_add_f32_e32 v110, 1.0, v110
	v_add_f32_e32 v111, 1.0, v111
	v_rcp_f32_e32 v110, v110
	v_rcp_f32_e32 v111, v111
	s_nop 0
	v_pk_mul_f32 v[106:107], v[106:107], v[110:111]
	s_nop 0
	v_pk_mul_f32 v[98:99], v[98:99], v[106:107]
	v_pk_mul_f32 v[106:107], v[108:109], v[118:119] op_sel_hi:[1,0]
	v_cvt_pk_bf16_f32 v104, v98, v99
	v_mul_f32_e32 v108, 0xbfb8aa3b, v106
	v_mul_f32_e32 v109, 0xbfb8aa3b, v107
	v_exp_f32_e32 v108, v108
	v_exp_f32_e32 v109, v109
	v_add_f32_e32 v108, 1.0, v108
	v_add_f32_e32 v109, 1.0, v109
	v_rcp_f32_e32 v108, v108
	v_rcp_f32_e32 v109, v109
	s_nop 0
	v_pk_mul_f32 v[106:107], v[106:107], v[108:109]
	s_nop 0
	v_pk_mul_f32 v[100:101], v[100:101], v[106:107]
	v_lshl_add_u64 v[106:107], v[116:117], 0, v[114:115]
	v_cvt_pk_bf16_f32 v105, v100, v101
	global_store_dwordx4 v[106:107], v[102:105], off
	v_mov_b64_e32 v[98:99], v[160:161]
	v_or_b32_e32 v101, 32, v142
	s_nop 0
	v_ffbh_u32_e32 v100, v99
	v_min_u32_e32 v100, 32, v100
	v_lshlrev_b64 v[98:99], v100, v[98:99]
	v_min_u32_e32 v98, 1, v98
	v_or_b32_e32 v98, v99, v98
	v_cvt_f32_u32_e32 v98, v98
	v_sub_u32_e32 v99, 32, v100
	v_ldexp_f32 v98, v98, v99
	v_fmamk_f32 v98, v98, 0x31800000, v219
	v_cmp_gt_f32_e32 vcc, s86, v98
	v_mul_f32_e32 v99, 0x4b800000, v98
	s_nop 0
	v_cndmask_b32_e32 v98, v98, v99, vcc
	v_rsq_f32_e32 v98, v98
	s_nop 0
	v_mul_f32_e32 v99, 0x45800000, v98
	v_cndmask_b32_e32 v100, v98, v99, vcc
	v_pk_mul_f32 v[94:95], v[94:95], v[100:101] op_sel_hi:[1,0]
	v_mad_i64_i32 v[98:99], s[22:23], v101, s83, v[146:147]
	v_mul_f32_e32 v101, 0xbfb8aa3b, v94
	v_exp_f32_e32 v101, v101
	s_nop 0
	v_add_f32_e32 v101, 1.0, v101
	v_rcp_f32_e32 v102, v101
	v_pk_mul_f32 v[86:87], v[86:87], v[100:101] op_sel_hi:[1,0]
	v_mul_f32_e32 v101, 0xbfb8aa3b, v95
	v_exp_f32_e32 v101, v101
	s_nop 0
	v_add_f32_e32 v101, 1.0, v101
	v_rcp_f32_e32 v103, v101
	v_pk_mul_f32 v[88:89], v[88:89], v[100:101] op_sel_hi:[1,0]
	v_pk_mul_f32 v[90:91], v[90:91], v[100:101] op_sel_hi:[1,0]
	v_pk_mul_f32 v[82:83], v[82:83], v[100:101] op_sel_hi:[1,0]
	v_pk_mul_f32 v[94:95], v[94:95], v[102:103]
	v_pk_mul_f32 v[84:85], v[84:85], v[100:101] op_sel_hi:[1,0]
	v_pk_mul_f32 v[86:87], v[86:87], v[94:95]
	v_pk_mul_f32 v[94:95], v[96:97], v[100:101] op_sel_hi:[1,0]
	v_cvt_pk_bf16_f32 v86, v86, v87
	v_mul_f32_e32 v96, 0xbfb8aa3b, v94
	v_mul_f32_e32 v97, 0xbfb8aa3b, v95
	v_exp_f32_e32 v96, v96
	v_exp_f32_e32 v97, v97
	v_add_f32_e32 v96, 1.0, v96
	v_add_f32_e32 v97, 1.0, v97
	v_rcp_f32_e32 v96, v96
	v_rcp_f32_e32 v97, v97
	s_nop 0
	v_pk_mul_f32 v[94:95], v[94:95], v[96:97]
	s_nop 0
	v_pk_mul_f32 v[88:89], v[88:89], v[94:95]
	v_mul_f32_e32 v94, 0xbfb8aa3b, v90
	v_mul_f32_e32 v95, 0xbfb8aa3b, v91
	v_exp_f32_e32 v94, v94
	v_exp_f32_e32 v95, v95
	v_cvt_pk_bf16_f32 v87, v88, v89
	v_add_f32_e32 v94, 1.0, v94
	v_add_f32_e32 v95, 1.0, v95
	v_rcp_f32_e32 v94, v94
	v_rcp_f32_e32 v95, v95
	s_nop 0
	v_pk_mul_f32 v[90:91], v[90:91], v[94:95]
	s_nop 0
	v_pk_mul_f32 v[82:83], v[82:83], v[90:91]
	v_pk_mul_f32 v[90:91], v[92:93], v[100:101] op_sel_hi:[1,0]
	v_cvt_pk_bf16_f32 v88, v82, v83
	v_mul_f32_e32 v92, 0xbfb8aa3b, v90
	v_mul_f32_e32 v93, 0xbfb8aa3b, v91
	v_exp_f32_e32 v92, v92
	v_exp_f32_e32 v93, v93
	v_add_f32_e32 v92, 1.0, v92
	v_add_f32_e32 v93, 1.0, v93
	v_rcp_f32_e32 v92, v92
	v_rcp_f32_e32 v93, v93
	s_nop 0
	v_pk_mul_f32 v[90:91], v[90:91], v[92:93]
	s_nop 0
	v_pk_mul_f32 v[84:85], v[84:85], v[90:91]
	v_lshl_add_u64 v[90:91], v[98:99], 0, v[114:115]
	v_cvt_pk_bf16_f32 v89, v84, v85
	global_store_dwordx4 v[90:91], v[86:89], off
	v_mov_b64_e32 v[82:83], v[162:163]
	v_or_b32_e32 v85, 48, v142
	s_nop 0
	v_ffbh_u32_e32 v84, v83
	v_min_u32_e32 v84, 32, v84
	v_lshlrev_b64 v[82:83], v84, v[82:83]
	v_min_u32_e32 v82, 1, v82
	v_or_b32_e32 v82, v83, v82
	v_cvt_f32_u32_e32 v82, v82
	v_sub_u32_e32 v83, 32, v84
	v_ldexp_f32 v82, v82, v83
	v_fmamk_f32 v82, v82, 0x31800000, v219
	v_cmp_gt_f32_e32 vcc, s86, v82
	v_mul_f32_e32 v83, 0x4b800000, v82
	s_nop 0
	v_cndmask_b32_e32 v82, v82, v83, vcc
	v_rsq_f32_e32 v82, v82
	s_nop 0
	v_mul_f32_e32 v83, 0x45800000, v82
	v_cndmask_b32_e32 v84, v82, v83, vcc
	v_pk_mul_f32 v[78:79], v[78:79], v[84:85] op_sel_hi:[1,0]
	v_mad_i64_i32 v[82:83], s[22:23], v85, s83, v[146:147]
	v_mul_f32_e32 v85, 0xbfb8aa3b, v78
	v_exp_f32_e32 v85, v85
	s_nop 0
	v_add_f32_e32 v85, 1.0, v85
	v_rcp_f32_e32 v86, v85
	v_pk_mul_f32 v[70:71], v[70:71], v[84:85] op_sel_hi:[1,0]
	v_mul_f32_e32 v85, 0xbfb8aa3b, v79
	v_exp_f32_e32 v85, v85
	s_nop 0
	v_add_f32_e32 v85, 1.0, v85
	v_rcp_f32_e32 v87, v85
	v_pk_mul_f32 v[72:73], v[72:73], v[84:85] op_sel_hi:[1,0]
	v_pk_mul_f32 v[74:75], v[74:75], v[84:85] op_sel_hi:[1,0]
	v_pk_mul_f32 v[66:67], v[66:67], v[84:85] op_sel_hi:[1,0]
	v_pk_mul_f32 v[78:79], v[78:79], v[86:87]
	v_pk_mul_f32 v[68:69], v[68:69], v[84:85] op_sel_hi:[1,0]
	v_pk_mul_f32 v[70:71], v[70:71], v[78:79]
	v_pk_mul_f32 v[78:79], v[80:81], v[84:85] op_sel_hi:[1,0]
	v_cvt_pk_bf16_f32 v70, v70, v71
	v_mul_f32_e32 v80, 0xbfb8aa3b, v78
	v_mul_f32_e32 v81, 0xbfb8aa3b, v79
	v_exp_f32_e32 v80, v80
	v_exp_f32_e32 v81, v81
	v_add_f32_e32 v80, 1.0, v80
	v_add_f32_e32 v81, 1.0, v81
	v_rcp_f32_e32 v80, v80
	v_rcp_f32_e32 v81, v81
	s_nop 0
	v_pk_mul_f32 v[78:79], v[78:79], v[80:81]
	s_nop 0
	v_pk_mul_f32 v[72:73], v[72:73], v[78:79]
	v_mul_f32_e32 v78, 0xbfb8aa3b, v74
	v_mul_f32_e32 v79, 0xbfb8aa3b, v75
	v_exp_f32_e32 v78, v78
	v_exp_f32_e32 v79, v79
	v_cvt_pk_bf16_f32 v71, v72, v73
	v_add_f32_e32 v78, 1.0, v78
	v_add_f32_e32 v79, 1.0, v79
	v_rcp_f32_e32 v78, v78
	v_rcp_f32_e32 v79, v79
	s_nop 0
	v_pk_mul_f32 v[74:75], v[74:75], v[78:79]
	s_nop 0
	v_pk_mul_f32 v[66:67], v[66:67], v[74:75]
	v_pk_mul_f32 v[74:75], v[76:77], v[84:85] op_sel_hi:[1,0]
	v_cvt_pk_bf16_f32 v72, v66, v67
	v_mul_f32_e32 v76, 0xbfb8aa3b, v74
	v_mul_f32_e32 v77, 0xbfb8aa3b, v75
	v_exp_f32_e32 v76, v76
	v_exp_f32_e32 v77, v77
	v_add_f32_e32 v76, 1.0, v76
	v_add_f32_e32 v77, 1.0, v77
	v_rcp_f32_e32 v76, v76
	v_rcp_f32_e32 v77, v77
	s_nop 0
	v_pk_mul_f32 v[74:75], v[74:75], v[76:77]
	s_nop 0
	v_pk_mul_f32 v[68:69], v[68:69], v[74:75]
	v_lshl_add_u64 v[74:75], v[82:83], 0, v[114:115]
	v_cvt_pk_bf16_f32 v73, v68, v69
	global_store_dwordx4 v[74:75], v[70:73], off
	v_mov_b64_e32 v[66:67], v[164:165]
	v_add_u32_e32 v69, 0x80, v142
	s_nop 0
	v_ffbh_u32_e32 v68, v67
	v_min_u32_e32 v68, 32, v68
	v_lshlrev_b64 v[66:67], v68, v[66:67]
	v_min_u32_e32 v66, 1, v66
	v_or_b32_e32 v66, v67, v66
	v_cvt_f32_u32_e32 v66, v66
	v_sub_u32_e32 v67, 32, v68
	v_ldexp_f32 v66, v66, v67
	v_fmamk_f32 v66, v66, 0x31800000, v219
	v_cmp_gt_f32_e32 vcc, s86, v66
	v_mul_f32_e32 v67, 0x4b800000, v66
	s_nop 0
	v_cndmask_b32_e32 v66, v66, v67, vcc
	v_rsq_f32_e32 v66, v66
	s_nop 0
	v_mul_f32_e32 v67, 0x45800000, v66
	v_cndmask_b32_e32 v68, v66, v67, vcc
	v_pk_mul_f32 v[62:63], v[62:63], v[68:69] op_sel_hi:[1,0]
	v_mad_i64_i32 v[66:67], s[22:23], v69, s83, v[146:147]
	v_mul_f32_e32 v69, 0xbfb8aa3b, v62
	v_exp_f32_e32 v69, v69
	s_nop 0
	v_add_f32_e32 v69, 1.0, v69
	v_rcp_f32_e32 v70, v69
	v_pk_mul_f32 v[54:55], v[54:55], v[68:69] op_sel_hi:[1,0]
	v_mul_f32_e32 v69, 0xbfb8aa3b, v63
	v_exp_f32_e32 v69, v69
	s_nop 0
	v_add_f32_e32 v69, 1.0, v69
	v_rcp_f32_e32 v71, v69
	v_pk_mul_f32 v[56:57], v[56:57], v[68:69] op_sel_hi:[1,0]
	v_pk_mul_f32 v[58:59], v[58:59], v[68:69] op_sel_hi:[1,0]
	v_pk_mul_f32 v[50:51], v[50:51], v[68:69] op_sel_hi:[1,0]
	v_pk_mul_f32 v[62:63], v[62:63], v[70:71]
	v_pk_mul_f32 v[52:53], v[52:53], v[68:69] op_sel_hi:[1,0]
	v_pk_mul_f32 v[54:55], v[54:55], v[62:63]
	v_pk_mul_f32 v[62:63], v[64:65], v[68:69] op_sel_hi:[1,0]
	v_cvt_pk_bf16_f32 v54, v54, v55
	v_mul_f32_e32 v64, 0xbfb8aa3b, v62
	v_mul_f32_e32 v65, 0xbfb8aa3b, v63
	v_exp_f32_e32 v64, v64
	v_exp_f32_e32 v65, v65
	v_add_f32_e32 v64, 1.0, v64
	v_add_f32_e32 v65, 1.0, v65
	v_rcp_f32_e32 v64, v64
	v_rcp_f32_e32 v65, v65
	s_nop 0
	v_pk_mul_f32 v[62:63], v[62:63], v[64:65]
	s_nop 0
	v_pk_mul_f32 v[56:57], v[56:57], v[62:63]
	v_mul_f32_e32 v62, 0xbfb8aa3b, v58
	v_mul_f32_e32 v63, 0xbfb8aa3b, v59
	v_exp_f32_e32 v62, v62
	v_exp_f32_e32 v63, v63
	v_cvt_pk_bf16_f32 v55, v56, v57
	v_add_f32_e32 v62, 1.0, v62
	v_add_f32_e32 v63, 1.0, v63
	v_rcp_f32_e32 v62, v62
	v_rcp_f32_e32 v63, v63
	s_nop 0
	v_pk_mul_f32 v[58:59], v[58:59], v[62:63]
	s_nop 0
	v_pk_mul_f32 v[50:51], v[50:51], v[58:59]
	v_pk_mul_f32 v[58:59], v[60:61], v[68:69] op_sel_hi:[1,0]
	v_cvt_pk_bf16_f32 v56, v50, v51
	v_mul_f32_e32 v60, 0xbfb8aa3b, v58
	v_mul_f32_e32 v61, 0xbfb8aa3b, v59
	v_exp_f32_e32 v60, v60
	v_exp_f32_e32 v61, v61
	v_add_f32_e32 v60, 1.0, v60
	v_add_f32_e32 v61, 1.0, v61
	v_rcp_f32_e32 v60, v60
	v_rcp_f32_e32 v61, v61
	s_nop 0
	v_pk_mul_f32 v[58:59], v[58:59], v[60:61]
	s_nop 0
	v_pk_mul_f32 v[52:53], v[52:53], v[58:59]
	v_lshl_add_u64 v[58:59], v[66:67], 0, v[114:115]
	v_cvt_pk_bf16_f32 v57, v52, v53
	global_store_dwordx4 v[58:59], v[54:57], off
	v_mov_b64_e32 v[50:51], v[166:167]
	v_add_u32_e32 v53, 0x90, v142
	s_nop 0
	v_ffbh_u32_e32 v52, v51
	v_min_u32_e32 v52, 32, v52
	v_lshlrev_b64 v[50:51], v52, v[50:51]
	v_min_u32_e32 v50, 1, v50
	v_or_b32_e32 v50, v51, v50
	v_cvt_f32_u32_e32 v50, v50
	v_sub_u32_e32 v51, 32, v52
	v_ldexp_f32 v50, v50, v51
	v_fmamk_f32 v50, v50, 0x31800000, v219
	v_cmp_gt_f32_e32 vcc, s86, v50
	v_mul_f32_e32 v51, 0x4b800000, v50
	s_nop 0
	v_cndmask_b32_e32 v50, v50, v51, vcc
	v_rsq_f32_e32 v50, v50
	s_nop 0
	v_mul_f32_e32 v51, 0x45800000, v50
	v_cndmask_b32_e32 v52, v50, v51, vcc
	v_pk_mul_f32 v[46:47], v[46:47], v[52:53] op_sel_hi:[1,0]
	v_mad_i64_i32 v[50:51], s[22:23], v53, s83, v[146:147]
	v_mul_f32_e32 v53, 0xbfb8aa3b, v46
	v_exp_f32_e32 v53, v53
	s_nop 0
	v_add_f32_e32 v53, 1.0, v53
	v_rcp_f32_e32 v54, v53
	v_pk_mul_f32 v[38:39], v[38:39], v[52:53] op_sel_hi:[1,0]
	v_mul_f32_e32 v53, 0xbfb8aa3b, v47
	v_exp_f32_e32 v53, v53
	s_nop 0
	v_add_f32_e32 v53, 1.0, v53
	v_rcp_f32_e32 v55, v53
	v_pk_mul_f32 v[40:41], v[40:41], v[52:53] op_sel_hi:[1,0]
	v_pk_mul_f32 v[42:43], v[42:43], v[52:53] op_sel_hi:[1,0]
	v_pk_mul_f32 v[34:35], v[34:35], v[52:53] op_sel_hi:[1,0]
	v_pk_mul_f32 v[46:47], v[46:47], v[54:55]
	v_pk_mul_f32 v[36:37], v[36:37], v[52:53] op_sel_hi:[1,0]
	v_pk_mul_f32 v[38:39], v[38:39], v[46:47]
	v_pk_mul_f32 v[46:47], v[48:49], v[52:53] op_sel_hi:[1,0]
	v_cvt_pk_bf16_f32 v38, v38, v39
	v_mul_f32_e32 v48, 0xbfb8aa3b, v46
	v_mul_f32_e32 v49, 0xbfb8aa3b, v47
	v_exp_f32_e32 v48, v48
	v_exp_f32_e32 v49, v49
	v_add_f32_e32 v48, 1.0, v48
	v_add_f32_e32 v49, 1.0, v49
	v_rcp_f32_e32 v48, v48
	v_rcp_f32_e32 v49, v49
	s_nop 0
	v_pk_mul_f32 v[46:47], v[46:47], v[48:49]
	s_nop 0
	v_pk_mul_f32 v[40:41], v[40:41], v[46:47]
	v_mul_f32_e32 v46, 0xbfb8aa3b, v42
	v_mul_f32_e32 v47, 0xbfb8aa3b, v43
	v_exp_f32_e32 v46, v46
	v_exp_f32_e32 v47, v47
	v_cvt_pk_bf16_f32 v39, v40, v41
	v_add_f32_e32 v46, 1.0, v46
	v_add_f32_e32 v47, 1.0, v47
	v_rcp_f32_e32 v46, v46
	v_rcp_f32_e32 v47, v47
	s_nop 0
	v_pk_mul_f32 v[42:43], v[42:43], v[46:47]
	s_nop 0
	v_pk_mul_f32 v[34:35], v[34:35], v[42:43]
	v_pk_mul_f32 v[42:43], v[44:45], v[52:53] op_sel_hi:[1,0]
	v_cvt_pk_bf16_f32 v40, v34, v35
	v_mul_f32_e32 v44, 0xbfb8aa3b, v42
	v_mul_f32_e32 v45, 0xbfb8aa3b, v43
	v_exp_f32_e32 v44, v44
	v_exp_f32_e32 v45, v45
	v_add_f32_e32 v44, 1.0, v44
	v_add_f32_e32 v45, 1.0, v45
	v_rcp_f32_e32 v44, v44
	v_rcp_f32_e32 v45, v45
	s_nop 0
	v_pk_mul_f32 v[42:43], v[42:43], v[44:45]
	s_nop 0
	v_pk_mul_f32 v[36:37], v[36:37], v[42:43]
	v_lshl_add_u64 v[42:43], v[50:51], 0, v[114:115]
	v_cvt_pk_bf16_f32 v41, v36, v37
	global_store_dwordx4 v[42:43], v[38:41], off
	v_mov_b64_e32 v[34:35], v[168:169]
	v_add_u32_e32 v37, 0xa0, v142
	s_nop 0
	v_ffbh_u32_e32 v36, v35
	v_min_u32_e32 v36, 32, v36
	v_lshlrev_b64 v[34:35], v36, v[34:35]
	v_min_u32_e32 v34, 1, v34
	v_or_b32_e32 v34, v35, v34
	v_cvt_f32_u32_e32 v34, v34
	v_sub_u32_e32 v35, 32, v36
	v_ldexp_f32 v34, v34, v35
	v_fmamk_f32 v34, v34, 0x31800000, v219
	v_cmp_gt_f32_e32 vcc, s86, v34
	v_mul_f32_e32 v35, 0x4b800000, v34
	s_nop 0
	v_cndmask_b32_e32 v34, v34, v35, vcc
	v_rsq_f32_e32 v34, v34
	s_nop 0
	v_mul_f32_e32 v35, 0x45800000, v34
	v_cndmask_b32_e32 v36, v34, v35, vcc
	v_pk_mul_f32 v[30:31], v[30:31], v[36:37] op_sel_hi:[1,0]
	v_mad_i64_i32 v[34:35], s[22:23], v37, s83, v[146:147]
	v_mul_f32_e32 v37, 0xbfb8aa3b, v30
	v_exp_f32_e32 v37, v37
	s_nop 0
	v_add_f32_e32 v37, 1.0, v37
	v_rcp_f32_e32 v38, v37
	v_pk_mul_f32 v[22:23], v[22:23], v[36:37] op_sel_hi:[1,0]
	v_mul_f32_e32 v37, 0xbfb8aa3b, v31
	v_exp_f32_e32 v37, v37
	s_nop 0
	v_add_f32_e32 v37, 1.0, v37
	v_rcp_f32_e32 v39, v37
	v_pk_mul_f32 v[24:25], v[24:25], v[36:37] op_sel_hi:[1,0]
	v_pk_mul_f32 v[26:27], v[26:27], v[36:37] op_sel_hi:[1,0]
	v_pk_mul_f32 v[18:19], v[18:19], v[36:37] op_sel_hi:[1,0]
	v_pk_mul_f32 v[30:31], v[30:31], v[38:39]
	v_pk_mul_f32 v[20:21], v[20:21], v[36:37] op_sel_hi:[1,0]
	v_pk_mul_f32 v[22:23], v[22:23], v[30:31]
	v_pk_mul_f32 v[30:31], v[32:33], v[36:37] op_sel_hi:[1,0]
	v_cvt_pk_bf16_f32 v22, v22, v23
	v_mul_f32_e32 v32, 0xbfb8aa3b, v30
	v_mul_f32_e32 v33, 0xbfb8aa3b, v31
	v_exp_f32_e32 v32, v32
	v_exp_f32_e32 v33, v33
	v_add_f32_e32 v32, 1.0, v32
	v_add_f32_e32 v33, 1.0, v33
	v_rcp_f32_e32 v32, v32
	v_rcp_f32_e32 v33, v33
	s_nop 0
	v_pk_mul_f32 v[30:31], v[30:31], v[32:33]
	s_nop 0
	v_pk_mul_f32 v[24:25], v[24:25], v[30:31]
	v_mul_f32_e32 v30, 0xbfb8aa3b, v26
	v_mul_f32_e32 v31, 0xbfb8aa3b, v27
	v_exp_f32_e32 v30, v30
	v_exp_f32_e32 v31, v31
	v_cvt_pk_bf16_f32 v23, v24, v25
	v_add_f32_e32 v30, 1.0, v30
	v_add_f32_e32 v31, 1.0, v31
	v_rcp_f32_e32 v30, v30
	v_rcp_f32_e32 v31, v31
	s_nop 0
	v_pk_mul_f32 v[26:27], v[26:27], v[30:31]
	s_nop 0
	v_pk_mul_f32 v[18:19], v[18:19], v[26:27]
	v_pk_mul_f32 v[26:27], v[28:29], v[36:37] op_sel_hi:[1,0]
	v_cvt_pk_bf16_f32 v24, v18, v19
	v_mul_f32_e32 v28, 0xbfb8aa3b, v26
	v_mul_f32_e32 v29, 0xbfb8aa3b, v27
	v_exp_f32_e32 v28, v28
	v_exp_f32_e32 v29, v29
	v_add_f32_e32 v28, 1.0, v28
	v_add_f32_e32 v29, 1.0, v29
	v_rcp_f32_e32 v28, v28
	v_rcp_f32_e32 v29, v29
	s_nop 0
	v_pk_mul_f32 v[26:27], v[26:27], v[28:29]
	s_nop 0
	v_pk_mul_f32 v[20:21], v[20:21], v[26:27]
	v_lshl_add_u64 v[26:27], v[34:35], 0, v[114:115]
	v_cvt_pk_bf16_f32 v25, v20, v21
	global_store_dwordx4 v[26:27], v[22:25], off
	v_mov_b64_e32 v[18:19], v[170:171]
	v_add_u32_e32 v20, 0xb0, v142
	s_nop 0
	v_ffbh_u32_e32 v21, v19
	v_min_u32_e32 v21, 32, v21
	v_lshlrev_b64 v[18:19], v21, v[18:19]
	v_min_u32_e32 v18, 1, v18
	v_or_b32_e32 v18, v19, v18
	v_cvt_f32_u32_e32 v18, v18
	v_sub_u32_e32 v19, 32, v21
	v_mad_i64_i32 v[20:21], s[22:23], v20, s83, v[146:147]
	v_ldexp_f32 v18, v18, v19
	v_fmamk_f32 v18, v18, 0x31800000, v219
	v_cmp_gt_f32_e32 vcc, s86, v18
	v_mul_f32_e32 v19, 0x4b800000, v18
	s_mov_b64 s[22:23], -1
	v_cndmask_b32_e32 v18, v18, v19, vcc
	v_rsq_f32_e32 v18, v18
	s_nop 0
	v_mul_f32_e32 v19, 0x45800000, v18
	v_cndmask_b32_e32 v18, v18, v19, vcc
	v_pk_mul_f32 v[14:15], v[14:15], v[18:19] op_sel_hi:[1,0]
	s_andn2_b64 vcc, exec, s[2:3]
	v_mul_f32_e32 v19, 0xbfb8aa3b, v14
	v_exp_f32_e32 v19, v19
	s_nop 0
	v_add_f32_e32 v19, 1.0, v19
	v_rcp_f32_e32 v22, v19
	v_pk_mul_f32 v[6:7], v[6:7], v[18:19] op_sel_hi:[1,0]
	v_mul_f32_e32 v19, 0xbfb8aa3b, v15
	v_exp_f32_e32 v19, v19
	s_nop 0
	v_add_f32_e32 v19, 1.0, v19
	v_rcp_f32_e32 v23, v19
	v_pk_mul_f32 v[8:9], v[8:9], v[18:19] op_sel_hi:[1,0]
	v_pk_mul_f32 v[10:11], v[10:11], v[18:19] op_sel_hi:[1,0]
	v_pk_mul_f32 v[2:3], v[2:3], v[18:19] op_sel_hi:[1,0]
	v_pk_mul_f32 v[14:15], v[14:15], v[22:23]
	v_pk_mul_f32 v[4:5], v[4:5], v[18:19] op_sel_hi:[1,0]
	v_pk_mul_f32 v[6:7], v[6:7], v[14:15]
	v_pk_mul_f32 v[14:15], v[16:17], v[18:19] op_sel_hi:[1,0]
	s_nop 0
	v_mul_f32_e32 v16, 0xbfb8aa3b, v14
	v_mul_f32_e32 v17, 0xbfb8aa3b, v15
	v_exp_f32_e32 v16, v16
	v_exp_f32_e32 v17, v17
	v_add_f32_e32 v16, 1.0, v16
	v_add_f32_e32 v17, 1.0, v17
	v_rcp_f32_e32 v16, v16
	v_rcp_f32_e32 v17, v17
	s_nop 0
	v_pk_mul_f32 v[14:15], v[14:15], v[16:17]
	s_nop 0
	v_pk_mul_f32 v[8:9], v[8:9], v[14:15]
	v_mul_f32_e32 v14, 0xbfb8aa3b, v10
	v_mul_f32_e32 v15, 0xbfb8aa3b, v11
	v_exp_f32_e32 v14, v14
	v_exp_f32_e32 v15, v15
	v_add_f32_e32 v14, 1.0, v14
	v_add_f32_e32 v15, 1.0, v15
	v_rcp_f32_e32 v14, v14
	v_rcp_f32_e32 v15, v15
	s_nop 0
	v_pk_mul_f32 v[10:11], v[10:11], v[14:15]
	s_nop 0
	v_pk_mul_f32 v[10:11], v[2:3], v[10:11]
	v_pk_mul_f32 v[2:3], v[12:13], v[18:19] op_sel_hi:[1,0]
	v_lshl_add_u64 v[14:15], v[20:21], 0, v[114:115]
	v_mul_f32_e32 v12, 0xbfb8aa3b, v2
	v_mul_f32_e32 v13, 0xbfb8aa3b, v3
	v_exp_f32_e32 v12, v12
	v_exp_f32_e32 v13, v13
	v_add_f32_e32 v12, 1.0, v12
	v_add_f32_e32 v13, 1.0, v13
	v_rcp_f32_e32 v12, v12
	v_rcp_f32_e32 v13, v13
	s_nop 0
	v_pk_mul_f32 v[2:3], v[2:3], v[12:13]
	s_nop 0
	v_pk_mul_f32 v[12:13], v[4:5], v[2:3]
	v_cvt_pk_bf16_f32 v2, v6, v7
	v_cvt_pk_bf16_f32 v3, v8, v9
	v_cvt_pk_bf16_f32 v4, v10, v11
	v_cvt_pk_bf16_f32 v5, v12, v13
	global_store_dwordx4 v[14:15], v[2:5], off
	s_cbranch_vccnz .LBB0_1176
	s_andn2_b64 vcc, exec, s[6:7]
	s_cbranch_vccnz .LBB0_1175
	s_barrier
	s_branch .LBB0_1175
